# K-loop: no instructions between last MFMA of a segment and its barrier (loop-end scalar updates hoisted before the MFMA segment, s_setprio dropped)
# speedup vs baseline: 1.0118x; 1.0068x over previous
; #define PG8_STAGE(bufoff, gbase, voff) do { _Pragma("unroll") for (int _i = 0; _i < 2; ++_i) \
;         __builtin_amdgcn_global_load_lds((const unsigned*)((const char*)(gbase) + (voff)[_i]), (LAS unsigned*)(lds + (bufoff) + ldsw + _i * 8192), 16, 0, 0); } while (0)
; #define PG8_LDA(dst, b, h) do { _Pragma("unroll") for (int m = 0; m < 4; ++m) _Pragma("unroll") for (int k = 0; k < 2; ++k) dst[m][k] = *(const LAS bf16x8*)(lds + PG8_SA(b, h) + aoff + m * 2048 + k * 1024); } while (0)
; #define PG8_WAIT_V(n) asm volatile("s_waitcnt vmcnt(" #n ")" ::: "memory")
; #define PG8_WAIT_L(n) asm volatile("s_waitcnt lgkmcnt(" #n ")" ::: "memory")
; __device__ __forceinline__ void gemm_phase(LAS unsigned char* lds, const Gemm g, const StaticOrder& S, const Epi& E) {
;     ...
;         for (int t = 0; t < nt; t += 2) {
;             const bool last = (t == nt - 2);
;             const char* a1 = cA + (size_t)(t + 1) * kstep;
;             const char* a2 = last ? nA : cA + (size_t)(t + 2) * kstep; const char* b2 = last ? nB : cB + (size_t)(t + 2) * kstep;
;             const char* a3 = a2 + kstep; const char* b3 = b2 + kstep;
;             PG8_LDB(B0, 0, 0); PG8_SCHED; PG8_LDA(At, 0, 0); PG8_STAGE(PG8_SA(1, 1), a1 + hstep, voffA);
;             PG8_WAIT_L(8); PG8_BAR; PG8_WAIT_L(0); PG8_MMA(0, 0, At, B0); PG8_BAR; PG8_SCHED;
;             PG8_LDB(B1, 0, 1); PG8_STAGE(PG8_SB(0, 0), b2, voffB);
;             PG8_BAR; PG8_WAIT_L(0); PG8_MMA(0, 1, At, B1); PG8_BAR;
;             PG8_LDA(At, 0, 1); PG8_STAGE(PG8_SA(0, 0), a2, voffA);
;             PG8_BAR; PG8_WAIT_L(0); PG8_MMA(1, 0, At, B0); PG8_BAR; PG8_SCHED;
;             PG8_STAGE(PG8_SB(0, 1), b2 + hstep, voffB);
;             PG8_WAIT_V(6); PG8_BAR; PG8_MMA(1, 1, At, B1); PG8_BAR;
;             PG8_LDB(B0, 1, 0); PG8_SCHED; PG8_LDA(At, 1, 0); PG8_STAGE(PG8_SA(0, 1), a2 + hstep, voffA);
;             PG8_WAIT_L(8); PG8_BAR; PG8_WAIT_L(0); PG8_MMA(0, 0, At, B0); PG8_BAR; PG8_SCHED;
;             PG8_LDB(B1, 1, 1); PG8_STAGE(PG8_SB(1, 0), b3, voffB);
;             PG8_BAR; PG8_WAIT_L(0); PG8_MMA(0, 1, At, B1); PG8_BAR;
;             PG8_LDA(At, 1, 1); PG8_STAGE(PG8_SA(1, 0), a3, voffA);
;             PG8_BAR; PG8_WAIT_L(0); PG8_MMA(1, 0, At, B0); PG8_BAR; PG8_SCHED;
;             PG8_STAGE(PG8_SB(1, 1), b3 + hstep, voffB);
;             PG8_WAIT_V(6); PG8_BAR; PG8_MMA(1, 1, At, B1); PG8_BAR;
.Lmy_q10_first:
	s_waitcnt lgkmcnt(4)
	s_barrier
	v_mfma_f32_16x16x32_bf16 v[126:129], v[130:133], v[146:149], v[126:129]
	v_mfma_f32_16x16x32_bf16 v[122:125], v[138:141], v[146:149], v[122:125]
	v_mfma_f32_16x16x32_bf16 v[118:121], v[130:133], v[154:157], v[118:121]
	v_mfma_f32_16x16x32_bf16 v[110:113], v[138:141], v[154:157], v[110:113]
	v_mfma_f32_16x16x32_bf16 v[102:105], v[130:133], v[162:165], v[102:105]
	v_mfma_f32_16x16x32_bf16 v[94:97], v[138:141], v[162:165], v[94:97]
	v_mfma_f32_16x16x32_bf16 v[86:89], v[130:133], v[170:173], v[86:89]
	v_mfma_f32_16x16x32_bf16 v[78:81], v[138:141], v[170:173], v[78:81]
	v_mfma_f32_16x16x32_bf16 v[126:129], v[134:137], v[150:153], v[126:129]
	v_mfma_f32_16x16x32_bf16 v[122:125], v[142:145], v[150:153], v[122:125]
	v_mfma_f32_16x16x32_bf16 v[118:121], v[134:137], v[158:161], v[118:121]
	v_mfma_f32_16x16x32_bf16 v[110:113], v[142:145], v[158:161], v[110:113]
	v_mfma_f32_16x16x32_bf16 v[102:105], v[134:137], v[166:169], v[102:105]
	v_mfma_f32_16x16x32_bf16 v[94:97], v[142:145], v[166:169], v[94:97]
	v_mfma_f32_16x16x32_bf16 v[86:89], v[134:137], v[174:177], v[86:89]
	v_mfma_f32_16x16x32_bf16 v[78:81], v[142:145], v[174:177], v[78:81]
	s_waitcnt lgkmcnt(0)
	v_mfma_f32_16x16x32_bf16 v[114:117], v[202:205], v[146:149], v[114:117]
	v_mfma_f32_16x16x32_bf16 v[106:109], v[210:213], v[146:149], v[106:109]
	v_mfma_f32_16x16x32_bf16 v[98:101], v[202:205], v[154:157], v[98:101]
	v_mfma_f32_16x16x32_bf16 v[90:93], v[210:213], v[154:157], v[90:93]
	v_mfma_f32_16x16x32_bf16 v[82:85], v[202:205], v[162:165], v[82:85]
	v_mfma_f32_16x16x32_bf16 v[74:77], v[210:213], v[162:165], v[74:77]
	v_mfma_f32_16x16x32_bf16 v[70:73], v[202:205], v[170:173], v[70:73]
	v_mfma_f32_16x16x32_bf16 v[66:69], v[210:213], v[170:173], v[66:69]
	v_mfma_f32_16x16x32_bf16 v[114:117], v[206:209], v[150:153], v[114:117]
	v_mfma_f32_16x16x32_bf16 v[106:109], v[214:217], v[150:153], v[106:109]
	v_mfma_f32_16x16x32_bf16 v[98:101], v[206:209], v[158:161], v[98:101]
	v_mfma_f32_16x16x32_bf16 v[90:93], v[214:217], v[158:161], v[90:93]
	v_mfma_f32_16x16x32_bf16 v[82:85], v[206:209], v[166:169], v[82:85]
	v_mfma_f32_16x16x32_bf16 v[74:77], v[214:217], v[166:169], v[74:77]
	v_mfma_f32_16x16x32_bf16 v[70:73], v[206:209], v[174:177], v[70:73]
	v_mfma_f32_16x16x32_bf16 v[66:69], v[214:217], v[174:177], v[66:69]
	s_barrier
	s_add_u32 s86, s56, 0x80
	s_addc_u32 s87, s57, 0
	s_add_u32 s88, s54, 0x80
	s_addc_u32 s89, s55, 0
	s_add_i32 m0, s65, 0x10000
	s_nop 0
	global_load_lds_dwordx4 v182, s[56:57]
	s_add_i32 m0, s65, 0x12000
	s_nop 0
	global_load_lds_dwordx4 v186, s[56:57]
	s_mov_b32 m0, s66
	s_nop 0
	global_load_lds_dwordx4 v180, s[54:55]
	s_mov_b32 m0, s67
	s_nop 0
	global_load_lds_dwordx4 v184, s[54:55]
	ds_read_b128 v[146:149], v245 offset:16384
	ds_read_b128 v[150:153], v245 offset:17408
	ds_read_b128 v[154:157], v245 offset:18432
	ds_read_b128 v[158:161], v245 offset:19456
	ds_read_b128 v[162:165], v245 offset:20480
	ds_read_b128 v[166:169], v245 offset:21504
	ds_read_b128 v[170:173], v245 offset:22528
	ds_read_b128 v[174:177], v245 offset:23552
	s_waitcnt vmcnt(6) lgkmcnt(0)
	s_barrier
	v_mfma_f32_16x16x32_bf16 v[62:65], v[130:133], v[146:149], v[62:65]
	v_mfma_f32_16x16x32_bf16 v[58:61], v[138:141], v[146:149], v[58:61]
	v_mfma_f32_16x16x32_bf16 v[54:57], v[130:133], v[154:157], v[54:57]
	v_mfma_f32_16x16x32_bf16 v[50:53], v[138:141], v[154:157], v[50:53]
	v_mfma_f32_16x16x32_bf16 v[38:41], v[130:133], v[162:165], v[38:41]
	v_mfma_f32_16x16x32_bf16 v[34:37], v[138:141], v[162:165], v[34:37]
	v_mfma_f32_16x16x32_bf16 v[22:25], v[130:133], v[170:173], v[22:25]
	v_mfma_f32_16x16x32_bf16 v[18:21], v[138:141], v[170:173], v[18:21]
	v_mfma_f32_16x16x32_bf16 v[62:65], v[134:137], v[150:153], v[62:65]
	v_mfma_f32_16x16x32_bf16 v[58:61], v[142:145], v[150:153], v[58:61]
	v_mfma_f32_16x16x32_bf16 v[54:57], v[134:137], v[158:161], v[54:57]
	v_mfma_f32_16x16x32_bf16 v[50:53], v[142:145], v[158:161], v[50:53]
	v_mfma_f32_16x16x32_bf16 v[38:41], v[134:137], v[166:169], v[38:41]
	v_mfma_f32_16x16x32_bf16 v[34:37], v[142:145], v[166:169], v[34:37]
	v_mfma_f32_16x16x32_bf16 v[22:25], v[134:137], v[174:177], v[22:25]
	v_mfma_f32_16x16x32_bf16 v[18:21], v[142:145], v[174:177], v[18:21]
	v_mfma_f32_16x16x32_bf16 v[46:49], v[202:205], v[146:149], v[46:49]
	v_mfma_f32_16x16x32_bf16 v[42:45], v[210:213], v[146:149], v[42:45]
	v_mfma_f32_16x16x32_bf16 v[30:33], v[202:205], v[154:157], v[30:33]
	v_mfma_f32_16x16x32_bf16 v[26:29], v[210:213], v[154:157], v[26:29]
	v_mfma_f32_16x16x32_bf16 v[14:17], v[202:205], v[162:165], v[14:17]
	v_mfma_f32_16x16x32_bf16 v[10:13], v[210:213], v[162:165], v[10:13]
	v_mfma_f32_16x16x32_bf16 v[6:9], v[202:205], v[170:173], v[6:9]
	v_mfma_f32_16x16x32_bf16 v[2:5], v[210:213], v[170:173], v[2:5]
	v_mfma_f32_16x16x32_bf16 v[46:49], v[206:209], v[150:153], v[46:49]
	v_mfma_f32_16x16x32_bf16 v[42:45], v[214:217], v[150:153], v[42:45]
	v_mfma_f32_16x16x32_bf16 v[30:33], v[206:209], v[158:161], v[30:33]
	v_mfma_f32_16x16x32_bf16 v[26:29], v[214:217], v[158:161], v[26:29]
	v_mfma_f32_16x16x32_bf16 v[14:17], v[206:209], v[166:169], v[14:17]
	v_mfma_f32_16x16x32_bf16 v[10:13], v[214:217], v[166:169], v[10:13]
	v_mfma_f32_16x16x32_bf16 v[6:9], v[206:209], v[174:177], v[6:9]
	v_mfma_f32_16x16x32_bf16 v[2:5], v[214:217], v[174:177], v[2:5]
	s_barrier
; #define PG8_STAGE(bufoff, gbase, voff) do { _Pragma("unroll") for (int _i = 0; _i < 2; ++_i) \
;         __builtin_amdgcn_global_load_lds((const unsigned*)((const char*)(gbase) + (voff)[_i]), (LAS unsigned*)(lds + (bufoff) + ldsw + _i * 8192), 16, 0, 0); } while (0)
; #define PG8_LDA(dst, b, h) do { _Pragma("unroll") for (int m = 0; m < 4; ++m) _Pragma("unroll") for (int k = 0; k < 2; ++k) dst[m][k] = *(const LAS bf16x8*)(lds + PG8_SA(b, h) + aoff + m * 2048 + k * 1024); } while (0)
; #define PG8_WAIT_V(n) asm volatile("s_waitcnt vmcnt(" #n ")" ::: "memory")
; #define PG8_WAIT_L(n) asm volatile("s_waitcnt lgkmcnt(" #n ")" ::: "memory")
; __device__ __forceinline__ void gemm_phase(LAS unsigned char* lds, const Gemm g, const StaticOrder& S, const Epi& E) {
;     ...
;         for (int t = 0; t < nt; t += 2) {
;             const bool last = (t == nt - 2);
;             const char* a1 = cA + (size_t)(t + 1) * kstep;
;             const char* a2 = last ? nA : cA + (size_t)(t + 2) * kstep; const char* b2 = last ? nB : cB + (size_t)(t + 2) * kstep;
;             const char* a3 = a2 + kstep; const char* b3 = b2 + kstep;
;             PG8_LDB(B0, 0, 0); PG8_SCHED; PG8_LDA(At, 0, 0); PG8_STAGE(PG8_SA(1, 1), a1 + hstep, voffA);
;             PG8_WAIT_L(8); PG8_BAR; PG8_WAIT_L(0); PG8_MMA(0, 0, At, B0); PG8_BAR; PG8_SCHED;
;             PG8_LDB(B1, 0, 1); PG8_STAGE(PG8_SB(0, 0), b2, voffB);
;             PG8_BAR; PG8_WAIT_L(0); PG8_MMA(0, 1, At, B1); PG8_BAR;
;             PG8_LDA(At, 0, 1); PG8_STAGE(PG8_SA(0, 0), a2, voffA);
;             PG8_BAR; PG8_WAIT_L(0); PG8_MMA(1, 0, At, B0); PG8_BAR; PG8_SCHED;
;             PG8_STAGE(PG8_SB(0, 1), b2 + hstep, voffB);
;             PG8_WAIT_V(6); PG8_BAR; PG8_MMA(1, 1, At, B1); PG8_BAR;
;             PG8_LDB(B0, 1, 0); PG8_SCHED; PG8_LDA(At, 1, 0); PG8_STAGE(PG8_SA(0, 1), a2 + hstep, voffA);
;             PG8_WAIT_L(8); PG8_BAR; PG8_WAIT_L(0); PG8_MMA(0, 0, At, B0); PG8_BAR; PG8_SCHED;
;             PG8_LDB(B1, 1, 1); PG8_STAGE(PG8_SB(1, 0), b3, voffB);
;             PG8_BAR; PG8_WAIT_L(0); PG8_MMA(0, 1, At, B1); PG8_BAR;
;             PG8_LDA(At, 1, 1); PG8_STAGE(PG8_SA(1, 0), a3, voffA);
;             PG8_BAR; PG8_WAIT_L(0); PG8_MMA(1, 0, At, B0); PG8_BAR; PG8_SCHED;
;             PG8_STAGE(PG8_SB(1, 1), b3 + hstep, voffB);
;             PG8_WAIT_V(6); PG8_BAR; PG8_MMA(1, 1, At, B1); PG8_BAR;
	s_add_u32 s56, s56, s48
	s_addc_u32 s57, s57, 0
	s_add_u32 s54, s54, s48
	s_addc_u32 s55, s55, 0
	v_add_u32_e32 v142, 0x18000, v244
	v_add_u32_e32 v178, 0x1c000, v244
	s_add_i32 m0, s65, 0x14000
	s_nop 0
	global_load_lds_dwordx4 v182, s[56:57]
	s_add_i32 m0, s65, 0x16000
	s_nop 0
	global_load_lds_dwordx4 v186, s[56:57]
	s_mov_b32 m0, s68
	s_nop 0
	global_load_lds_dwordx4 v180, s[54:55]
	s_mov_b32 m0, s69
	s_nop 0
	global_load_lds_dwordx4 v184, s[54:55]
	ds_read_b128 v[130:133], v142
	ds_read_b128 v[134:137], v142 offset:1024
	ds_read_b128 v[138:141], v142 offset:2048
	ds_read_b128 v[142:145], v142 offset:3072
	ds_read_b128 v[146:149], v245 offset:32768
	ds_read_b128 v[150:153], v245 offset:33792
	ds_read_b128 v[154:157], v245 offset:34816
	ds_read_b128 v[158:161], v245 offset:35840
	ds_read_b128 v[162:165], v245 offset:36864
	ds_read_b128 v[166:169], v245 offset:37888
	ds_read_b128 v[170:173], v245 offset:38912
	ds_read_b128 v[174:177], v245 offset:39936
	s_waitcnt lgkmcnt(8)
	ds_read_b128 v[202:205], v178
	ds_read_b128 v[206:209], v178 offset:1024
	ds_read_b128 v[210:213], v178 offset:2048
	ds_read_b128 v[214:217], v178 offset:3072
	s_waitcnt vmcnt(8) lgkmcnt(4)
	s_barrier
	v_mfma_f32_16x16x32_bf16 v[126:129], v[130:133], v[146:149], v[126:129]
	v_mfma_f32_16x16x32_bf16 v[122:125], v[138:141], v[146:149], v[122:125]
	v_mfma_f32_16x16x32_bf16 v[118:121], v[130:133], v[154:157], v[118:121]
	v_mfma_f32_16x16x32_bf16 v[110:113], v[138:141], v[154:157], v[110:113]
	v_mfma_f32_16x16x32_bf16 v[102:105], v[130:133], v[162:165], v[102:105]
	v_mfma_f32_16x16x32_bf16 v[94:97], v[138:141], v[162:165], v[94:97]
	v_mfma_f32_16x16x32_bf16 v[86:89], v[130:133], v[170:173], v[86:89]
	v_mfma_f32_16x16x32_bf16 v[78:81], v[138:141], v[170:173], v[78:81]
	v_mfma_f32_16x16x32_bf16 v[126:129], v[134:137], v[150:153], v[126:129]
	v_mfma_f32_16x16x32_bf16 v[122:125], v[142:145], v[150:153], v[122:125]
	v_mfma_f32_16x16x32_bf16 v[118:121], v[134:137], v[158:161], v[118:121]
	v_mfma_f32_16x16x32_bf16 v[110:113], v[142:145], v[158:161], v[110:113]
	v_mfma_f32_16x16x32_bf16 v[102:105], v[134:137], v[166:169], v[102:105]
	v_mfma_f32_16x16x32_bf16 v[94:97], v[142:145], v[166:169], v[94:97]
	v_mfma_f32_16x16x32_bf16 v[86:89], v[134:137], v[174:177], v[86:89]
	v_mfma_f32_16x16x32_bf16 v[78:81], v[142:145], v[174:177], v[78:81]
	s_waitcnt lgkmcnt(0)
	v_mfma_f32_16x16x32_bf16 v[114:117], v[202:205], v[146:149], v[114:117]
	v_mfma_f32_16x16x32_bf16 v[106:109], v[210:213], v[146:149], v[106:109]
	v_mfma_f32_16x16x32_bf16 v[98:101], v[202:205], v[154:157], v[98:101]
	v_mfma_f32_16x16x32_bf16 v[90:93], v[210:213], v[154:157], v[90:93]
	v_mfma_f32_16x16x32_bf16 v[82:85], v[202:205], v[162:165], v[82:85]
	v_mfma_f32_16x16x32_bf16 v[74:77], v[210:213], v[162:165], v[74:77]
	v_mfma_f32_16x16x32_bf16 v[70:73], v[202:205], v[170:173], v[70:73]
	v_mfma_f32_16x16x32_bf16 v[66:69], v[210:213], v[170:173], v[66:69]
	v_mfma_f32_16x16x32_bf16 v[114:117], v[206:209], v[150:153], v[114:117]
	v_mfma_f32_16x16x32_bf16 v[106:109], v[214:217], v[150:153], v[106:109]
	v_mfma_f32_16x16x32_bf16 v[98:101], v[206:209], v[158:161], v[98:101]
	v_mfma_f32_16x16x32_bf16 v[90:93], v[214:217], v[158:161], v[90:93]
	v_mfma_f32_16x16x32_bf16 v[82:85], v[206:209], v[166:169], v[82:85]
	v_mfma_f32_16x16x32_bf16 v[74:77], v[214:217], v[166:169], v[74:77]
	v_mfma_f32_16x16x32_bf16 v[70:73], v[206:209], v[174:177], v[70:73]
	v_mfma_f32_16x16x32_bf16 v[66:69], v[214:217], v[174:177], v[66:69]
	s_barrier
	s_add_i32 m0, s65, 0x18000
	s_nop 0
	global_load_lds_dwordx4 v182, s[86:87]
	s_add_i32 m0, s65, 0x1a000
	s_nop 0
	global_load_lds_dwordx4 v186, s[86:87]
	s_mov_b32 m0, s70
	s_nop 0
	global_load_lds_dwordx4 v180, s[88:89]
	s_mov_b32 m0, s71
	s_nop 0
	global_load_lds_dwordx4 v184, s[88:89]
	ds_read_b128 v[146:149], v245 offset:49152
	ds_read_b128 v[150:153], v245 offset:50176
	ds_read_b128 v[154:157], v245 offset:51200
	ds_read_b128 v[158:161], v245 offset:52224
	ds_read_b128 v[162:165], v245 offset:53248
	ds_read_b128 v[166:169], v245 offset:54272
	ds_read_b128 v[170:173], v245 offset:55296
	ds_read_b128 v[174:177], v245 offset:56320
	s_cmp_ge_u32 s61, s72
	s_cbranch_scc1 .Lmy_q21_last
	s_waitcnt vmcnt(6)
	s_branch .Lmy_q21_cont

; #define PG8_STAGE(bufoff, gbase, voff) do { _Pragma("unroll") for (int _i = 0; _i < 2; ++_i) \
;         __builtin_amdgcn_global_load_lds((const unsigned*)((const char*)(gbase) + (voff)[_i]), (LAS unsigned*)(lds + (bufoff) + ldsw + _i * 8192), 16, 0, 0); } while (0)
; #define PG8_LDA(dst, b, h) do { _Pragma("unroll") for (int m = 0; m < 4; ++m) _Pragma("unroll") for (int k = 0; k < 2; ++k) dst[m][k] = *(const LAS bf16x8*)(lds + PG8_SA(b, h) + aoff + m * 2048 + k * 1024); } while (0)
; #define PG8_LDB(dst, b, h) do { _Pragma("unroll") for (int n = 0; n < 2; ++n) _Pragma("unroll") for (int k = 0; k < 2; ++k) dst[n][k] = *(const LAS bf16x8*)(lds + PG8_SB(b, h) + boff + n * 2048 + k * 1024); } while (0)
; #define PG8_MMA(ai, bj, At, Bt) do { __builtin_amdgcn_s_setprio(1); _Pragma("unroll") for (int m = 0; m < 4; ++m) _Pragma("unroll") for (int n = 0; n < 2; ++n) _Pragma("unroll") for (int k = 0; k < 2; ++k) \
;         acc[ai][bj][m][n] = __builtin_amdgcn_mfma_f32_16x16x32_bf16(Bt[n][k], At[m][k], acc[ai][bj][m][n], 0, 0, 0); __builtin_amdgcn_s_setprio(0); } while (0)
; #define PG8_WAIT_V(n) asm volatile("s_waitcnt vmcnt(" #n ")" ::: "memory")
; #define PG8_WAIT_L(n) asm volatile("s_waitcnt lgkmcnt(" #n ")" ::: "memory")
; #define PG8_BAR __builtin_amdgcn_s_barrier()
; #define PG8_SCHED __builtin_amdgcn_sched_barrier(0)
; __device__ __forceinline__ void gemm_phase(LAS unsigned char* lds, const Gemm g, const StaticOrder& S, const Epi& E) {
;     ...
;             PG8_WAIT_V(6); PG8_BAR; PG8_MMA(1, 1, At, B1); PG8_BAR;
;             PG8_LDB(B0, 1, 0); PG8_SCHED; PG8_LDA(At, 1, 0); PG8_STAGE(PG8_SA(0, 1), a2 + hstep, voffA);
;             PG8_WAIT_L(8); PG8_BAR; PG8_WAIT_L(0); PG8_MMA(0, 0, At, B0); PG8_BAR; PG8_SCHED;
;             PG8_LDB(B1, 1, 1); PG8_STAGE(PG8_SB(1, 0), b3, voffB);
;             PG8_BAR; PG8_WAIT_L(0); PG8_MMA(0, 1, At, B1); PG8_BAR;
;             PG8_LDA(At, 1, 1); PG8_STAGE(PG8_SA(1, 0), a3, voffA);
;             PG8_BAR; PG8_WAIT_L(0); PG8_MMA(1, 0, At, B0); PG8_BAR; PG8_SCHED;
;             PG8_STAGE(PG8_SB(1, 1), b3 + hstep, voffB);
;             PG8_WAIT_V(6); PG8_BAR; PG8_MMA(1, 1, At, B1); PG8_BAR;
;         }
;         E(acc, cur, wr, wc, fr, fq);
;         if (!has_next) break;
.Lmy_q21_cont:
	s_add_u32 s44, s44, 0x100
	s_addc_u32 s45, s45, 0
	s_add_u32 s59, s59, 0x100
	s_addc_u32 s60, s60, 0
	s_mov_b32 s54, s61
	s_waitcnt lgkmcnt(0)
	s_cmp_ge_u32 s61, s72
	s_barrier
	v_mfma_f32_16x16x32_bf16 v[62:65], v[130:133], v[146:149], v[62:65]
	v_mfma_f32_16x16x32_bf16 v[58:61], v[138:141], v[146:149], v[58:61]
	v_mfma_f32_16x16x32_bf16 v[54:57], v[130:133], v[154:157], v[54:57]
	v_mfma_f32_16x16x32_bf16 v[50:53], v[138:141], v[154:157], v[50:53]
	v_mfma_f32_16x16x32_bf16 v[38:41], v[130:133], v[162:165], v[38:41]
	v_mfma_f32_16x16x32_bf16 v[34:37], v[138:141], v[162:165], v[34:37]
	v_mfma_f32_16x16x32_bf16 v[22:25], v[130:133], v[170:173], v[22:25]
	v_mfma_f32_16x16x32_bf16 v[18:21], v[138:141], v[170:173], v[18:21]
	v_mfma_f32_16x16x32_bf16 v[62:65], v[134:137], v[150:153], v[62:65]
	v_mfma_f32_16x16x32_bf16 v[58:61], v[142:145], v[150:153], v[58:61]
	v_mfma_f32_16x16x32_bf16 v[54:57], v[134:137], v[158:161], v[54:57]
	v_mfma_f32_16x16x32_bf16 v[50:53], v[142:145], v[158:161], v[50:53]
	v_mfma_f32_16x16x32_bf16 v[38:41], v[134:137], v[166:169], v[38:41]
	v_mfma_f32_16x16x32_bf16 v[34:37], v[142:145], v[166:169], v[34:37]
	v_mfma_f32_16x16x32_bf16 v[22:25], v[134:137], v[174:177], v[22:25]
	v_mfma_f32_16x16x32_bf16 v[18:21], v[142:145], v[174:177], v[18:21]
	v_mfma_f32_16x16x32_bf16 v[46:49], v[202:205], v[146:149], v[46:49]
	v_mfma_f32_16x16x32_bf16 v[42:45], v[210:213], v[146:149], v[42:45]
	v_mfma_f32_16x16x32_bf16 v[30:33], v[202:205], v[154:157], v[30:33]
	v_mfma_f32_16x16x32_bf16 v[26:29], v[210:213], v[154:157], v[26:29]
	v_mfma_f32_16x16x32_bf16 v[14:17], v[202:205], v[162:165], v[14:17]
	v_mfma_f32_16x16x32_bf16 v[10:13], v[210:213], v[162:165], v[10:13]
	v_mfma_f32_16x16x32_bf16 v[6:9], v[202:205], v[170:173], v[6:9]
	v_mfma_f32_16x16x32_bf16 v[2:5], v[210:213], v[170:173], v[2:5]
	v_mfma_f32_16x16x32_bf16 v[46:49], v[206:209], v[150:153], v[46:49]
	v_mfma_f32_16x16x32_bf16 v[42:45], v[214:217], v[150:153], v[42:45]
	v_mfma_f32_16x16x32_bf16 v[30:33], v[206:209], v[158:161], v[30:33]
	v_mfma_f32_16x16x32_bf16 v[26:29], v[214:217], v[158:161], v[26:29]
	v_mfma_f32_16x16x32_bf16 v[14:17], v[206:209], v[166:169], v[14:17]
	v_mfma_f32_16x16x32_bf16 v[10:13], v[214:217], v[166:169], v[10:13]
	v_mfma_f32_16x16x32_bf16 v[6:9], v[206:209], v[174:177], v[6:9]
	v_mfma_f32_16x16x32_bf16 v[2:5], v[214:217], v[174:177], v[2:5]
	s_barrier
	s_cbranch_scc0 .LBB0_555
	s_cmpk_gt_u32 s64, 0xff
	s_cbranch_scc1 .Lmy_e1
	s_barrier
